# FFN-up (SwiGLU) epilogue activation stores marked non-temporal (streamed once, keep operand panels in L2)
# speedup vs baseline: 1.0033x; 1.0032x over previous
; DI float silu(float x) { return x * sigm(x); }
; DI u32x4 pack8(f32x4 a, f32x4 b) { u32x4 w; w.x = pk2(a[0], a[1]); w.y = pk2(a[2], a[3]); w.z = pk2(b[0], b[1]); w.w = pk2(b[2], b[3]); return w; }
; #define EPI_ROWS(ai, m) _Pragma("unroll") for (int ai = 0; ai < 2; ++ai) _Pragma("unroll") for (int m = 0; m < 4; ++m)
; #define EPI_RSTD8(rr, ssqp, invn) float rr[2][4]; EPI_ROWS(ai, m) rr[ai][m] = (ssqp)[epi_row(u, ai, wr, m, fr)]; EPI_FENCE(); EPI_ROWS(ai, m) rr[ai][m] = rstd_of(rr[ai][m], invn);
; DI float rstd_of(float ssq, float invn) { return __builtin_amdgcn_rsqf(ssq * invn + EPS); }
;     DI void operator()(const Acc& acc, const Unit& u, int wr, int wc, int fr, int fq) const {
;         const int cb = u.pn * 128 + wc * 32 + 8 * fq;
;         EPI_RSTD8(rr, ssq, 1.0f / D)
;         EPI_ROWS(ai, m) { const int row = epi_row(u, ai, wr, m, fr); const float r = rr[ai][m];
;             f32x4 v[2];
; #pragma unroll
;             for (int n = 0; n < 2; ++n)
; #pragma unroll
;                 for (int j = 0; j < 4; ++j) v[n][j] = silu(acc[ai][0][m][n][j] * r) * (acc[ai][1][m][n][j] * r);
;             *(u32x4*)(act + (size_t)row * FF + cb) = pack8(v[0], v[1]); }
.LBB0_231:
	s_lshl_b32 s31, s40, 8
	s_add_i32 s31, s31, s95
	v_mbcnt_lo_u32_b32 v146, -1, 0
	v_mbcnt_hi_u32_b32 v146, -1, v146
	s_andn2_b64 vcc, exec, s[6:7]
	v_and_or_b32 v170, v146, 15, s31
	v_ashrrev_i32_e32 v171, 31, v170
	v_lshl_add_u64 v[144:145], v[170:171], 2, s[12:13]
	global_load_dword v150, v[144:145], off
	v_or_b32_e32 v168, 16, v170
	v_ashrrev_i32_e32 v169, 31, v168
	v_or_b32_e32 v164, 32, v170
	v_or_b32_e32 v160, 48, v170
	v_add_u32_e32 v156, 0x80, v170
	v_add_u32_e32 v152, 0x90, v170
	v_add_u32_e32 v148, 0xa0, v170
	v_add_u32_e32 v144, 0xb0, v170
	v_lshl_add_u64 v[166:167], v[168:169], 2, s[12:13]
	v_ashrrev_i32_e32 v165, 31, v164
	v_ashrrev_i32_e32 v161, 31, v160
	v_ashrrev_i32_e32 v157, 31, v156
	v_ashrrev_i32_e32 v153, 31, v152
	v_ashrrev_i32_e32 v149, 31, v148
	v_ashrrev_i32_e32 v145, 31, v144
	v_lshl_add_u64 v[172:173], v[164:165], 2, s[12:13]
	v_lshl_add_u64 v[174:175], v[160:161], 2, s[12:13]
	v_lshl_add_u64 v[176:177], v[156:157], 2, s[12:13]
	v_lshl_add_u64 v[178:179], v[152:153], 2, s[12:13]
	v_lshl_add_u64 v[180:181], v[148:149], 2, s[12:13]
	v_lshl_add_u64 v[182:183], v[144:145], 2, s[12:13]
	global_load_dword v145, v[166:167], off
	global_load_dword v149, v[172:173], off
	global_load_dword v153, v[174:175], off
	global_load_dword v154, v[176:177], off
	global_load_dword v157, v[178:179], off
	global_load_dword v158, v[180:181], off
	global_load_dword v161, v[182:183], off
	s_lshl_b32 s31, s58, 7
	v_ashrrev_i32_e32 v146, 1, v146
	s_or_b32 s31, s31, s22
	v_and_b32_e32 v146, -8, v146
	v_add_u32_e32 v172, s31, v146
	v_ashrrev_i32_e32 v173, 31, v172
	s_mov_b64 s[6:7], -1
	s_waitcnt vmcnt(0)
	v_fmamk_f32 v146, v150, 0x3a800000, v163
	v_rsq_f32_e32 v174, v146
	v_fmamk_f32 v145, v145, 0x3a800000, v163
	v_fmamk_f32 v146, v149, 0x3a800000, v163
	v_fmamk_f32 v149, v153, 0x3a800000, v163
	v_fmamk_f32 v150, v154, 0x3a800000, v163
	v_fmamk_f32 v153, v157, 0x3a800000, v163
	v_fmamk_f32 v157, v158, 0x3a800000, v163
	v_fmamk_f32 v161, v161, 0x3a800000, v163
	v_pk_mul_f32 v[124:125], v[124:125], v[174:175] op_sel_hi:[1,0]
	v_pk_mul_f32 v[126:127], v[126:127], v[174:175] op_sel_hi:[1,0]
	v_pk_mul_f32 v[120:121], v[120:121], v[174:175] op_sel_hi:[1,0]
	v_rsq_f32_e32 v176, v145
	v_rsq_f32_e32 v166, v146
	v_rsq_f32_e32 v162, v149
	v_rsq_f32_e32 v158, v150
	v_rsq_f32_e32 v154, v153
	v_rsq_f32_e32 v150, v157
	v_rsq_f32_e32 v146, v161
	v_pk_mul_f32 v[122:123], v[122:123], v[174:175] op_sel_hi:[1,0]
	v_mul_f32_e32 v145, 0xbfb8aa3b, v124
	v_mul_f32_e32 v149, 0xbfb8aa3b, v125
	v_mul_f32_e32 v153, 0xbfb8aa3b, v126
	v_mul_f32_e32 v157, 0xbfb8aa3b, v127
	v_mul_f32_e32 v161, 0xbfb8aa3b, v120
	v_mul_f32_e32 v165, 0xbfb8aa3b, v121
	v_mul_f32_e32 v167, 0xbfb8aa3b, v122
	v_mul_f32_e32 v169, 0xbfb8aa3b, v123
	v_exp_f32_e32 v145, v145
	v_exp_f32_e32 v149, v149
	v_exp_f32_e32 v153, v153
	v_exp_f32_e32 v157, v157
	v_exp_f32_e32 v161, v161
	v_exp_f32_e32 v165, v165
	v_exp_f32_e32 v167, v167
	v_exp_f32_e32 v169, v169
	v_add_f32_e32 v145, 1.0, v145
	v_add_f32_e32 v149, 1.0, v149
	v_add_f32_e32 v153, 1.0, v153
	v_add_f32_e32 v157, 1.0, v157
	v_add_f32_e32 v161, 1.0, v161
	v_add_f32_e32 v165, 1.0, v165
	v_add_f32_e32 v167, 1.0, v167
	v_add_f32_e32 v169, 1.0, v169
	v_rcp_f32_e32 v178, v145
	v_rcp_f32_e32 v179, v149
	v_rcp_f32_e32 v180, v153
	v_rcp_f32_e32 v181, v157
	v_rcp_f32_e32 v182, v161
	v_rcp_f32_e32 v183, v165
	v_rcp_f32_e32 v184, v167
	v_rcp_f32_e32 v185, v169
	v_pk_mul_f32 v[116:117], v[116:117], v[174:175] op_sel_hi:[1,0]
	v_pk_mul_f32 v[118:119], v[118:119], v[174:175] op_sel_hi:[1,0]
	v_pk_mul_f32 v[112:113], v[112:113], v[174:175] op_sel_hi:[1,0]
	v_pk_mul_f32 v[124:125], v[124:125], v[178:179]
	v_pk_mul_f32 v[126:127], v[126:127], v[180:181]
	v_pk_mul_f32 v[120:121], v[120:121], v[182:183]
	v_pk_mul_f32 v[116:117], v[116:117], v[124:125]
	v_pk_mul_f32 v[118:119], v[118:119], v[126:127]
	v_pk_mul_f32 v[112:113], v[112:113], v[120:121]
	v_pk_mul_f32 v[120:121], v[122:123], v[184:185]
	v_pk_mul_f32 v[114:115], v[114:115], v[174:175] op_sel_hi:[1,0]
	v_cvt_pk_bf16_f32 v116, v116, v117
	v_pk_mul_f32 v[114:115], v[114:115], v[120:121]
	v_cvt_pk_bf16_f32 v117, v118, v119
	v_cvt_pk_bf16_f32 v118, v112, v113
	v_mov_b64_e32 v[112:113], s[14:15]
	v_cvt_pk_bf16_f32 v119, v114, v115
	v_mad_i64_i32 v[120:121], s[42:43], v170, s55, v[112:113]
	v_lshlrev_b64 v[114:115], 1, v[172:173]
	v_pk_mul_f32 v[108:109], v[108:109], v[176:177] op_sel_hi:[1,0]
	v_lshl_add_u64 v[120:121], v[120:121], 0, v[114:115]
	v_mul_f32_e32 v122, 0xbfb8aa3b, v108
	v_mul_f32_e32 v123, 0xbfb8aa3b, v109
	v_pk_mul_f32 v[110:111], v[110:111], v[176:177] op_sel_hi:[1,0]
	v_exp_f32_e32 v122, v122
	v_exp_f32_e32 v123, v123
	global_store_dwordx4 v[120:121], v[116:119], off nt
	v_pk_mul_f32 v[100:101], v[100:101], v[176:177] op_sel_hi:[1,0]
	v_pk_mul_f32 v[104:105], v[104:105], v[176:177] op_sel_hi:[1,0]
	v_mul_f32_e32 v118, 0xbfb8aa3b, v110
	v_mul_f32_e32 v119, 0xbfb8aa3b, v111
	v_exp_f32_e32 v118, v118
	v_exp_f32_e32 v119, v119
	v_add_f32_e32 v116, 1.0, v122
	v_add_f32_e32 v117, 1.0, v123
	v_rcp_f32_e32 v116, v116
	v_rcp_f32_e32 v117, v117
	v_add_f32_e32 v118, 1.0, v118
	v_add_f32_e32 v119, 1.0, v119
	v_rcp_f32_e32 v118, v118
	v_rcp_f32_e32 v119, v119
	v_pk_mul_f32 v[108:109], v[108:109], v[116:117]
	v_pk_mul_f32 v[102:103], v[102:103], v[176:177] op_sel_hi:[1,0]
	v_pk_mul_f32 v[100:101], v[100:101], v[108:109]
	v_pk_mul_f32 v[108:109], v[110:111], v[118:119]
	v_mul_f32_e32 v110, 0xbfb8aa3b, v104
	v_mul_f32_e32 v111, 0xbfb8aa3b, v105
	v_exp_f32_e32 v110, v110
	v_exp_f32_e32 v111, v111
	v_pk_mul_f32 v[106:107], v[106:107], v[176:177] op_sel_hi:[1,0]
	v_pk_mul_f32 v[102:103], v[102:103], v[108:109]
; DI float silu(float x) { return x * sigm(x); }
; DI u32x4 pack8(f32x4 a, f32x4 b) { u32x4 w; w.x = pk2(a[0], a[1]); w.y = pk2(a[2], a[3]); w.z = pk2(b[0], b[1]); w.w = pk2(b[2], b[3]); return w; }
; #define EPI_ROWS(ai, m) _Pragma("unroll") for (int ai = 0; ai < 2; ++ai) _Pragma("unroll") for (int m = 0; m < 4; ++m)
;     DI void operator()(const Acc& acc, const Unit& u, int wr, int wc, int fr, int fq) const {
;     ...
;         EPI_ROWS(ai, m) { const int row = epi_row(u, ai, wr, m, fr); const float r = rr[ai][m];
;             f32x4 v[2];
; #pragma unroll
;             for (int n = 0; n < 2; ++n)
; #pragma unroll
;                 for (int j = 0; j < 4; ++j) v[n][j] = silu(acc[ai][0][m][n][j] * r) * (acc[ai][1][m][n][j] * r);
;             *(u32x4*)(act + (size_t)row * FF + cb) = pack8(v[0], v[1]); }
	v_add_f32_e32 v108, 1.0, v110
	v_add_f32_e32 v109, 1.0, v111
	v_mul_f32_e32 v110, 0xbfb8aa3b, v106
	v_mul_f32_e32 v111, 0xbfb8aa3b, v107
	v_exp_f32_e32 v110, v110
	v_exp_f32_e32 v111, v111
	v_rcp_f32_e32 v108, v108
	v_rcp_f32_e32 v109, v109
	v_add_f32_e32 v110, 1.0, v110
	v_add_f32_e32 v111, 1.0, v111
	v_rcp_f32_e32 v110, v110
	v_rcp_f32_e32 v111, v111
	v_pk_mul_f32 v[104:105], v[104:105], v[108:109]
	v_pk_mul_f32 v[96:97], v[96:97], v[176:177] op_sel_hi:[1,0]
	v_pk_mul_f32 v[98:99], v[98:99], v[176:177] op_sel_hi:[1,0]
	v_pk_mul_f32 v[104:105], v[96:97], v[104:105]
	v_pk_mul_f32 v[96:97], v[106:107], v[110:111]
	v_pk_mul_f32 v[92:93], v[92:93], v[166:167] op_sel_hi:[1,0]
	v_pk_mul_f32 v[106:107], v[98:99], v[96:97]
	v_cvt_pk_bf16_f32 v96, v100, v101
	v_mad_i64_i32 v[100:101], s[42:43], v168, s55, v[112:113]
	v_cvt_pk_bf16_f32 v97, v102, v103
	v_cvt_pk_bf16_f32 v98, v104, v105
	v_cvt_pk_bf16_f32 v99, v106, v107
	v_lshl_add_u64 v[100:101], v[100:101], 0, v[114:115]
	v_mul_f32_e32 v102, 0xbfb8aa3b, v92
	v_mul_f32_e32 v103, 0xbfb8aa3b, v93
	v_pk_mul_f32 v[94:95], v[94:95], v[166:167] op_sel_hi:[1,0]
	v_exp_f32_e32 v102, v102
	v_exp_f32_e32 v103, v103
	global_store_dwordx4 v[100:101], v[96:99], off nt
	v_pk_mul_f32 v[84:85], v[84:85], v[166:167] op_sel_hi:[1,0]
	v_pk_mul_f32 v[88:89], v[88:89], v[166:167] op_sel_hi:[1,0]
	v_mul_f32_e32 v98, 0xbfb8aa3b, v94
	v_mul_f32_e32 v99, 0xbfb8aa3b, v95
	v_exp_f32_e32 v98, v98
	v_exp_f32_e32 v99, v99
	v_add_f32_e32 v96, 1.0, v102
	v_add_f32_e32 v97, 1.0, v103
	v_rcp_f32_e32 v96, v96
	v_rcp_f32_e32 v97, v97
	v_add_f32_e32 v98, 1.0, v98
	v_add_f32_e32 v99, 1.0, v99
	v_rcp_f32_e32 v98, v98
	v_rcp_f32_e32 v99, v99
	v_pk_mul_f32 v[92:93], v[92:93], v[96:97]
	v_pk_mul_f32 v[86:87], v[86:87], v[166:167] op_sel_hi:[1,0]
	v_pk_mul_f32 v[84:85], v[84:85], v[92:93]
	v_pk_mul_f32 v[92:93], v[94:95], v[98:99]
	v_mul_f32_e32 v94, 0xbfb8aa3b, v88
	v_mul_f32_e32 v95, 0xbfb8aa3b, v89
	v_exp_f32_e32 v94, v94
	v_exp_f32_e32 v95, v95
	v_pk_mul_f32 v[90:91], v[90:91], v[166:167] op_sel_hi:[1,0]
	v_pk_mul_f32 v[86:87], v[86:87], v[92:93]
	v_add_f32_e32 v92, 1.0, v94
	v_add_f32_e32 v93, 1.0, v95
	v_mul_f32_e32 v94, 0xbfb8aa3b, v90
	v_mul_f32_e32 v95, 0xbfb8aa3b, v91
	v_exp_f32_e32 v94, v94
	v_exp_f32_e32 v95, v95
	v_rcp_f32_e32 v92, v92
	v_rcp_f32_e32 v93, v93
	v_add_f32_e32 v94, 1.0, v94
	v_add_f32_e32 v95, 1.0, v95
	v_rcp_f32_e32 v94, v94
	v_rcp_f32_e32 v95, v95
	v_pk_mul_f32 v[88:89], v[88:89], v[92:93]
	v_pk_mul_f32 v[80:81], v[80:81], v[166:167] op_sel_hi:[1,0]
	v_pk_mul_f32 v[82:83], v[82:83], v[166:167] op_sel_hi:[1,0]
	v_pk_mul_f32 v[88:89], v[80:81], v[88:89]
	v_pk_mul_f32 v[80:81], v[90:91], v[94:95]
	v_pk_mul_f32 v[76:77], v[76:77], v[162:163] op_sel_hi:[1,0]
	v_pk_mul_f32 v[90:91], v[82:83], v[80:81]
	v_cvt_pk_bf16_f32 v80, v84, v85
	v_mad_i64_i32 v[84:85], s[42:43], v164, s55, v[112:113]
	v_cvt_pk_bf16_f32 v81, v86, v87
	v_cvt_pk_bf16_f32 v82, v88, v89
	v_cvt_pk_bf16_f32 v83, v90, v91
	v_lshl_add_u64 v[84:85], v[84:85], 0, v[114:115]
	v_mul_f32_e32 v86, 0xbfb8aa3b, v76
	v_mul_f32_e32 v87, 0xbfb8aa3b, v77
	v_pk_mul_f32 v[78:79], v[78:79], v[162:163] op_sel_hi:[1,0]
	v_exp_f32_e32 v86, v86
	v_exp_f32_e32 v87, v87
	global_store_dwordx4 v[84:85], v[80:83], off nt
	v_pk_mul_f32 v[68:69], v[68:69], v[162:163] op_sel_hi:[1,0]
	v_pk_mul_f32 v[72:73], v[72:73], v[162:163] op_sel_hi:[1,0]
	v_mul_f32_e32 v82, 0xbfb8aa3b, v78
	v_mul_f32_e32 v83, 0xbfb8aa3b, v79
	v_exp_f32_e32 v82, v82
	v_exp_f32_e32 v83, v83
	v_add_f32_e32 v80, 1.0, v86
	v_add_f32_e32 v81, 1.0, v87
	v_rcp_f32_e32 v80, v80
	v_rcp_f32_e32 v81, v81
	v_add_f32_e32 v82, 1.0, v82
	v_add_f32_e32 v83, 1.0, v83
	v_rcp_f32_e32 v82, v82
	v_rcp_f32_e32 v83, v83
	v_pk_mul_f32 v[76:77], v[76:77], v[80:81]
	v_pk_mul_f32 v[70:71], v[70:71], v[162:163] op_sel_hi:[1,0]
	v_pk_mul_f32 v[68:69], v[68:69], v[76:77]
	v_pk_mul_f32 v[76:77], v[78:79], v[82:83]
	v_mul_f32_e32 v78, 0xbfb8aa3b, v72
	v_mul_f32_e32 v79, 0xbfb8aa3b, v73
	v_exp_f32_e32 v78, v78
	v_exp_f32_e32 v79, v79
	v_pk_mul_f32 v[74:75], v[74:75], v[162:163] op_sel_hi:[1,0]
	v_pk_mul_f32 v[70:71], v[70:71], v[76:77]
	v_add_f32_e32 v76, 1.0, v78
	v_add_f32_e32 v77, 1.0, v79
	v_mul_f32_e32 v78, 0xbfb8aa3b, v74
	v_mul_f32_e32 v79, 0xbfb8aa3b, v75
	v_exp_f32_e32 v78, v78
	v_exp_f32_e32 v79, v79
	v_rcp_f32_e32 v76, v76
	v_rcp_f32_e32 v77, v77
	v_add_f32_e32 v78, 1.0, v78
	v_add_f32_e32 v79, 1.0, v79
	v_rcp_f32_e32 v78, v78
	v_rcp_f32_e32 v79, v79
	v_pk_mul_f32 v[72:73], v[72:73], v[76:77]
	v_pk_mul_f32 v[64:65], v[64:65], v[162:163] op_sel_hi:[1,0]
	v_pk_mul_f32 v[66:67], v[66:67], v[162:163] op_sel_hi:[1,0]
	v_pk_mul_f32 v[72:73], v[64:65], v[72:73]
	v_pk_mul_f32 v[64:65], v[74:75], v[78:79]
	v_pk_mul_f32 v[60:61], v[60:61], v[158:159] op_sel_hi:[1,0]
	v_pk_mul_f32 v[74:75], v[66:67], v[64:65]
	v_cvt_pk_bf16_f32 v64, v68, v69
	v_mad_i64_i32 v[68:69], s[42:43], v160, s55, v[112:113]
	v_cvt_pk_bf16_f32 v65, v70, v71
	v_cvt_pk_bf16_f32 v66, v72, v73
	v_cvt_pk_bf16_f32 v67, v74, v75
	v_lshl_add_u64 v[68:69], v[68:69], 0, v[114:115]
	v_mul_f32_e32 v70, 0xbfb8aa3b, v60
	v_mul_f32_e32 v71, 0xbfb8aa3b, v61
	v_pk_mul_f32 v[62:63], v[62:63], v[158:159] op_sel_hi:[1,0]
	v_exp_f32_e32 v70, v70
	v_exp_f32_e32 v71, v71
	global_store_dwordx4 v[68:69], v[64:67], off nt
	v_pk_mul_f32 v[52:53], v[52:53], v[158:159] op_sel_hi:[1,0]
	v_pk_mul_f32 v[56:57], v[56:57], v[158:159] op_sel_hi:[1,0]
	v_mul_f32_e32 v66, 0xbfb8aa3b, v62
	v_mul_f32_e32 v67, 0xbfb8aa3b, v63
	v_exp_f32_e32 v66, v66
	v_exp_f32_e32 v67, v67
	v_add_f32_e32 v64, 1.0, v70
	v_add_f32_e32 v65, 1.0, v71
	v_rcp_f32_e32 v64, v64
	v_rcp_f32_e32 v65, v65
	v_add_f32_e32 v66, 1.0, v66
; DI float silu(float x) { return x * sigm(x); }
; DI u32x4 pack8(f32x4 a, f32x4 b) { u32x4 w; w.x = pk2(a[0], a[1]); w.y = pk2(a[2], a[3]); w.z = pk2(b[0], b[1]); w.w = pk2(b[2], b[3]); return w; }
; #define EPI_ROWS(ai, m) _Pragma("unroll") for (int ai = 0; ai < 2; ++ai) _Pragma("unroll") for (int m = 0; m < 4; ++m)
;     DI void operator()(const Acc& acc, const Unit& u, int wr, int wc, int fr, int fq) const {
;     ...
;         EPI_ROWS(ai, m) { const int row = epi_row(u, ai, wr, m, fr); const float r = rr[ai][m];
;             f32x4 v[2];
; #pragma unroll
;             for (int n = 0; n < 2; ++n)
; #pragma unroll
;                 for (int j = 0; j < 4; ++j) v[n][j] = silu(acc[ai][0][m][n][j] * r) * (acc[ai][1][m][n][j] * r);
;             *(u32x4*)(act + (size_t)row * FF + cb) = pack8(v[0], v[1]); }
	v_add_f32_e32 v67, 1.0, v67
	v_rcp_f32_e32 v66, v66
	v_rcp_f32_e32 v67, v67
	v_pk_mul_f32 v[60:61], v[60:61], v[64:65]
	v_pk_mul_f32 v[54:55], v[54:55], v[158:159] op_sel_hi:[1,0]
	v_pk_mul_f32 v[52:53], v[52:53], v[60:61]
	v_pk_mul_f32 v[60:61], v[62:63], v[66:67]
	v_mul_f32_e32 v62, 0xbfb8aa3b, v56
	v_mul_f32_e32 v63, 0xbfb8aa3b, v57
	v_exp_f32_e32 v62, v62
	v_exp_f32_e32 v63, v63
	v_pk_mul_f32 v[58:59], v[58:59], v[158:159] op_sel_hi:[1,0]
	v_pk_mul_f32 v[54:55], v[54:55], v[60:61]
	v_add_f32_e32 v60, 1.0, v62
	v_add_f32_e32 v61, 1.0, v63
	v_mul_f32_e32 v62, 0xbfb8aa3b, v58
	v_mul_f32_e32 v63, 0xbfb8aa3b, v59
	v_exp_f32_e32 v62, v62
	v_exp_f32_e32 v63, v63
	v_rcp_f32_e32 v60, v60
	v_rcp_f32_e32 v61, v61
	v_add_f32_e32 v62, 1.0, v62
	v_add_f32_e32 v63, 1.0, v63
	v_rcp_f32_e32 v62, v62
	v_rcp_f32_e32 v63, v63
	v_pk_mul_f32 v[56:57], v[56:57], v[60:61]
	v_pk_mul_f32 v[48:49], v[48:49], v[158:159] op_sel_hi:[1,0]
	v_pk_mul_f32 v[50:51], v[50:51], v[158:159] op_sel_hi:[1,0]
	v_pk_mul_f32 v[56:57], v[48:49], v[56:57]
	v_pk_mul_f32 v[48:49], v[58:59], v[62:63]
	v_pk_mul_f32 v[44:45], v[44:45], v[154:155] op_sel_hi:[1,0]
	v_pk_mul_f32 v[58:59], v[50:51], v[48:49]
	v_cvt_pk_bf16_f32 v48, v52, v53
	v_mad_i64_i32 v[52:53], s[42:43], v156, s55, v[112:113]
	v_cvt_pk_bf16_f32 v49, v54, v55
	v_cvt_pk_bf16_f32 v50, v56, v57
	v_cvt_pk_bf16_f32 v51, v58, v59
	v_lshl_add_u64 v[52:53], v[52:53], 0, v[114:115]
	v_mul_f32_e32 v54, 0xbfb8aa3b, v44
	v_mul_f32_e32 v55, 0xbfb8aa3b, v45
	v_pk_mul_f32 v[46:47], v[46:47], v[154:155] op_sel_hi:[1,0]
	v_exp_f32_e32 v54, v54
	v_exp_f32_e32 v55, v55
	global_store_dwordx4 v[52:53], v[48:51], off nt
	v_pk_mul_f32 v[36:37], v[36:37], v[154:155] op_sel_hi:[1,0]
	v_pk_mul_f32 v[40:41], v[40:41], v[154:155] op_sel_hi:[1,0]
	v_mul_f32_e32 v50, 0xbfb8aa3b, v46
	v_mul_f32_e32 v51, 0xbfb8aa3b, v47
	v_exp_f32_e32 v50, v50
	v_exp_f32_e32 v51, v51
	v_add_f32_e32 v48, 1.0, v54
	v_add_f32_e32 v49, 1.0, v55
	v_rcp_f32_e32 v48, v48
	v_rcp_f32_e32 v49, v49
	v_add_f32_e32 v50, 1.0, v50
	v_add_f32_e32 v51, 1.0, v51
	v_rcp_f32_e32 v50, v50
	v_rcp_f32_e32 v51, v51
	v_pk_mul_f32 v[44:45], v[44:45], v[48:49]
	v_pk_mul_f32 v[38:39], v[38:39], v[154:155] op_sel_hi:[1,0]
	v_pk_mul_f32 v[36:37], v[36:37], v[44:45]
	v_pk_mul_f32 v[44:45], v[46:47], v[50:51]
	v_mul_f32_e32 v46, 0xbfb8aa3b, v40
	v_mul_f32_e32 v47, 0xbfb8aa3b, v41
	v_exp_f32_e32 v46, v46
	v_exp_f32_e32 v47, v47
	v_pk_mul_f32 v[42:43], v[42:43], v[154:155] op_sel_hi:[1,0]
	v_pk_mul_f32 v[38:39], v[38:39], v[44:45]
	v_add_f32_e32 v44, 1.0, v46
	v_add_f32_e32 v45, 1.0, v47
	v_mul_f32_e32 v46, 0xbfb8aa3b, v42
	v_mul_f32_e32 v47, 0xbfb8aa3b, v43
	v_exp_f32_e32 v46, v46
	v_exp_f32_e32 v47, v47
	v_rcp_f32_e32 v44, v44
	v_rcp_f32_e32 v45, v45
	v_add_f32_e32 v46, 1.0, v46
	v_add_f32_e32 v47, 1.0, v47
	v_rcp_f32_e32 v46, v46
	v_rcp_f32_e32 v47, v47
	v_pk_mul_f32 v[40:41], v[40:41], v[44:45]
	v_pk_mul_f32 v[32:33], v[32:33], v[154:155] op_sel_hi:[1,0]
	v_pk_mul_f32 v[34:35], v[34:35], v[154:155] op_sel_hi:[1,0]
	v_pk_mul_f32 v[40:41], v[32:33], v[40:41]
	v_pk_mul_f32 v[32:33], v[42:43], v[46:47]
	v_pk_mul_f32 v[28:29], v[28:29], v[150:151] op_sel_hi:[1,0]
	v_pk_mul_f32 v[42:43], v[34:35], v[32:33]
	v_cvt_pk_bf16_f32 v32, v36, v37
	v_mad_i64_i32 v[36:37], s[42:43], v152, s55, v[112:113]
	v_cvt_pk_bf16_f32 v33, v38, v39
	v_cvt_pk_bf16_f32 v34, v40, v41
	v_cvt_pk_bf16_f32 v35, v42, v43
	v_lshl_add_u64 v[36:37], v[36:37], 0, v[114:115]
	v_mul_f32_e32 v38, 0xbfb8aa3b, v28
	v_mul_f32_e32 v39, 0xbfb8aa3b, v29
	v_pk_mul_f32 v[30:31], v[30:31], v[150:151] op_sel_hi:[1,0]
	v_exp_f32_e32 v38, v38
	v_exp_f32_e32 v39, v39
	global_store_dwordx4 v[36:37], v[32:35], off nt
	v_pk_mul_f32 v[20:21], v[20:21], v[150:151] op_sel_hi:[1,0]
	v_pk_mul_f32 v[24:25], v[24:25], v[150:151] op_sel_hi:[1,0]
; DI float silu(float x) { return x * sigm(x); }
; DI int lane_id() { int l; asm volatile("v_mbcnt_lo_u32_b32 %0, -1, 0\n\tv_mbcnt_hi_u32_b32 %0, -1, %0" : "=v"(l)); return l; }
; DI u32x4 pack8(f32x4 a, f32x4 b) { u32x4 w; w.x = pk2(a[0], a[1]); w.y = pk2(a[2], a[3]); w.z = pk2(b[0], b[1]); w.w = pk2(b[2], b[3]); return w; }
; #define PG8_BAR __builtin_amdgcn_s_barrier()
; #define EPI_ROWS(ai, m) _Pragma("unroll") for (int ai = 0; ai < 2; ++ai) _Pragma("unroll") for (int m = 0; m < 4; ++m)
; template <class Epi>
; DI void gemm_phase(LAS unsigned char* lds, const int wid, const Gemm g, const Order& S, const Epi& E) {
;     ...
;         if (wr == 0) PG8_BAR;
;         { const int le = lane_id(); E(acc, cur, wr, wc, le & 15, le >> 4); }
;         if (!has_next) break;
; #pragma unroll
;         for (int a = 0; a < 2; ++a)
; #pragma unroll
;             for (int b = 0; b < 2; ++b)
; #pragma unroll
;                 for (int m = 0; m < 4; ++m)
; #pragma unroll
;                     for (int n = 0; n < 2; ++n) acc[a][b][m][n] = (f32x4){0.f, 0.f, 0.f, 0.f};
;         cur = nxt; cA = nA; cB = nB; ++ui;
;         if (wr == 1) PG8_BAR;
;     DI void operator()(const Acc& acc, const Unit& u, int wr, int wc, int fr, int fq) const {
;     ...
;         EPI_ROWS(ai, m) { const int row = epi_row(u, ai, wr, m, fr); const float r = rr[ai][m];
;             f32x4 v[2];
; #pragma unroll
;             for (int n = 0; n < 2; ++n)
; #pragma unroll
;                 for (int j = 0; j < 4; ++j) v[n][j] = silu(acc[ai][0][m][n][j] * r) * (acc[ai][1][m][n][j] * r);
;             *(u32x4*)(act + (size_t)row * FF + cb) = pack8(v[0], v[1]); }
	v_mul_f32_e32 v34, 0xbfb8aa3b, v30
	v_mul_f32_e32 v35, 0xbfb8aa3b, v31
	v_exp_f32_e32 v34, v34
	v_exp_f32_e32 v35, v35
	v_add_f32_e32 v32, 1.0, v38
	v_add_f32_e32 v33, 1.0, v39
	v_rcp_f32_e32 v32, v32
	v_rcp_f32_e32 v33, v33
	v_add_f32_e32 v34, 1.0, v34
	v_add_f32_e32 v35, 1.0, v35
	v_rcp_f32_e32 v34, v34
	v_rcp_f32_e32 v35, v35
	v_pk_mul_f32 v[28:29], v[28:29], v[32:33]
	v_pk_mul_f32 v[22:23], v[22:23], v[150:151] op_sel_hi:[1,0]
	v_pk_mul_f32 v[20:21], v[20:21], v[28:29]
	v_pk_mul_f32 v[28:29], v[30:31], v[34:35]
	v_mul_f32_e32 v30, 0xbfb8aa3b, v24
	v_mul_f32_e32 v31, 0xbfb8aa3b, v25
	v_exp_f32_e32 v30, v30
	v_exp_f32_e32 v31, v31
	v_pk_mul_f32 v[26:27], v[26:27], v[150:151] op_sel_hi:[1,0]
	v_pk_mul_f32 v[22:23], v[22:23], v[28:29]
	v_add_f32_e32 v28, 1.0, v30
	v_add_f32_e32 v29, 1.0, v31
	v_mul_f32_e32 v30, 0xbfb8aa3b, v26
	v_mul_f32_e32 v31, 0xbfb8aa3b, v27
	v_exp_f32_e32 v30, v30
	v_exp_f32_e32 v31, v31
	v_rcp_f32_e32 v28, v28
	v_rcp_f32_e32 v29, v29
	v_add_f32_e32 v30, 1.0, v30
	v_add_f32_e32 v31, 1.0, v31
	v_rcp_f32_e32 v30, v30
	v_rcp_f32_e32 v31, v31
	v_pk_mul_f32 v[24:25], v[24:25], v[28:29]
	v_pk_mul_f32 v[16:17], v[16:17], v[150:151] op_sel_hi:[1,0]
	v_pk_mul_f32 v[18:19], v[18:19], v[150:151] op_sel_hi:[1,0]
	v_pk_mul_f32 v[24:25], v[16:17], v[24:25]
	v_pk_mul_f32 v[16:17], v[26:27], v[30:31]
	v_pk_mul_f32 v[12:13], v[12:13], v[146:147] op_sel_hi:[1,0]
	v_pk_mul_f32 v[26:27], v[18:19], v[16:17]
	v_cvt_pk_bf16_f32 v16, v20, v21
	v_mad_i64_i32 v[20:21], s[42:43], v148, s55, v[112:113]
	v_cvt_pk_bf16_f32 v17, v22, v23
	v_cvt_pk_bf16_f32 v18, v24, v25
	v_cvt_pk_bf16_f32 v19, v26, v27
	v_lshl_add_u64 v[20:21], v[20:21], 0, v[114:115]
	v_mul_f32_e32 v22, 0xbfb8aa3b, v12
	v_mul_f32_e32 v23, 0xbfb8aa3b, v13
	v_pk_mul_f32 v[14:15], v[14:15], v[146:147] op_sel_hi:[1,0]
	v_exp_f32_e32 v22, v22
	v_exp_f32_e32 v23, v23
	global_store_dwordx4 v[20:21], v[16:19], off nt
	v_pk_mul_f32 v[4:5], v[4:5], v[146:147] op_sel_hi:[1,0]
	v_pk_mul_f32 v[8:9], v[8:9], v[146:147] op_sel_hi:[1,0]
	v_mul_f32_e32 v18, 0xbfb8aa3b, v14
	v_mul_f32_e32 v19, 0xbfb8aa3b, v15
	v_exp_f32_e32 v18, v18
	v_exp_f32_e32 v19, v19
	v_add_f32_e32 v16, 1.0, v22
	v_add_f32_e32 v17, 1.0, v23
	v_rcp_f32_e32 v16, v16
	v_rcp_f32_e32 v17, v17
	v_add_f32_e32 v18, 1.0, v18
	v_add_f32_e32 v19, 1.0, v19
	v_rcp_f32_e32 v18, v18
	v_rcp_f32_e32 v19, v19
	v_pk_mul_f32 v[12:13], v[12:13], v[16:17]
	v_pk_mul_f32 v[6:7], v[6:7], v[146:147] op_sel_hi:[1,0]
	v_pk_mul_f32 v[4:5], v[4:5], v[12:13]
	v_pk_mul_f32 v[12:13], v[14:15], v[18:19]
	v_mul_f32_e32 v14, 0xbfb8aa3b, v8
	v_mul_f32_e32 v15, 0xbfb8aa3b, v9
	v_exp_f32_e32 v14, v14
	v_exp_f32_e32 v15, v15
	v_pk_mul_f32 v[10:11], v[10:11], v[146:147] op_sel_hi:[1,0]
	v_pk_mul_f32 v[6:7], v[6:7], v[12:13]
	v_add_f32_e32 v12, 1.0, v14
	v_add_f32_e32 v13, 1.0, v15
	v_mul_f32_e32 v14, 0xbfb8aa3b, v10
	v_mul_f32_e32 v15, 0xbfb8aa3b, v11
	v_exp_f32_e32 v14, v14
	v_exp_f32_e32 v15, v15
	v_rcp_f32_e32 v12, v12
	v_rcp_f32_e32 v13, v13
	v_add_f32_e32 v14, 1.0, v14
	v_add_f32_e32 v15, 1.0, v15
	v_rcp_f32_e32 v14, v14
	v_rcp_f32_e32 v15, v15
	v_pk_mul_f32 v[8:9], v[8:9], v[12:13]
	v_pk_mul_f32 v[0:1], v[0:1], v[146:147] op_sel_hi:[1,0]
	v_pk_mul_f32 v[2:3], v[2:3], v[146:147] op_sel_hi:[1,0]
	v_pk_mul_f32 v[8:9], v[0:1], v[8:9]
	v_pk_mul_f32 v[0:1], v[10:11], v[14:15]
	s_nop 0
	v_pk_mul_f32 v[10:11], v[2:3], v[0:1]
	v_cvt_pk_bf16_f32 v0, v4, v5
	v_mad_i64_i32 v[4:5], s[42:43], v144, s55, v[112:113]
	v_cvt_pk_bf16_f32 v1, v6, v7
	v_cvt_pk_bf16_f32 v2, v8, v9
	v_cvt_pk_bf16_f32 v3, v10, v11
	v_lshl_add_u64 v[4:5], v[4:5], 0, v[114:115]
	global_store_dwordx4 v[4:5], v[0:3], off nt
	s_cbranch_vccnz .LBB0_224
	s_andn2_b64 vcc, exec, s[10:11]
	s_cbranch_vccnz .LBB0_223
	s_barrier
	s_branch .LBB0_223

; DI float silu(float x) { return x * sigm(x); }
; DI u32x4 pack8(f32x4 a, f32x4 b) { u32x4 w; w.x = pk2(a[0], a[1]); w.y = pk2(a[2], a[3]); w.z = pk2(b[0], b[1]); w.w = pk2(b[2], b[3]); return w; }
; #define EPI_ROWS(ai, m) _Pragma("unroll") for (int ai = 0; ai < 2; ++ai) _Pragma("unroll") for (int m = 0; m < 4; ++m)
; #define EPI_RSTD8(rr, ssqp, invn) float rr[2][4]; EPI_ROWS(ai, m) rr[ai][m] = (ssqp)[epi_row(u, ai, wr, m, fr)]; EPI_FENCE(); EPI_ROWS(ai, m) rr[ai][m] = rstd_of(rr[ai][m], invn);
; DI float rstd_of(float ssq, float invn) { return __builtin_amdgcn_rsqf(ssq * invn + EPS); }
;     DI void operator()(const Acc& acc, const Unit& u, int wr, int wc, int fr, int fq) const {
;         const int cb = u.pn * 128 + wc * 32 + 8 * fq;
;         EPI_RSTD8(rr, ssq, 1.0f / D)
;         EPI_ROWS(ai, m) { const int row = epi_row(u, ai, wr, m, fr); const float r = rr[ai][m];
;             f32x4 v[2];
; #pragma unroll
;             for (int n = 0; n < 2; ++n)
; #pragma unroll
;                 for (int j = 0; j < 4; ++j) v[n][j] = silu(acc[ai][0][m][n][j] * r) * (acc[ai][1][m][n][j] * r);
;             *(u32x4*)(act + (size_t)row * FF + cb) = pack8(v[0], v[1]); }
.LBB0_1339:
	s_lshl_b32 s27, s36, 8
	s_add_i32 s27, s27, s95
	v_mbcnt_lo_u32_b32 v146, -1, 0
	v_mbcnt_hi_u32_b32 v146, -1, v146
	s_andn2_b64 vcc, exec, s[8:9]
	v_and_or_b32 v170, v146, 15, s27
	v_ashrrev_i32_e32 v171, 31, v170
	v_lshl_add_u64 v[144:145], v[170:171], 2, s[12:13]
	global_load_dword v150, v[144:145], off
	v_or_b32_e32 v168, 16, v170
	v_ashrrev_i32_e32 v169, 31, v168
	v_or_b32_e32 v164, 32, v170
	v_or_b32_e32 v160, 48, v170
	v_add_u32_e32 v156, 0x80, v170
	v_add_u32_e32 v152, 0x90, v170
	v_add_u32_e32 v148, 0xa0, v170
	v_add_u32_e32 v144, 0xb0, v170
	v_lshl_add_u64 v[166:167], v[168:169], 2, s[12:13]
	v_ashrrev_i32_e32 v165, 31, v164
	v_ashrrev_i32_e32 v161, 31, v160
	v_ashrrev_i32_e32 v157, 31, v156
	v_ashrrev_i32_e32 v153, 31, v152
	v_ashrrev_i32_e32 v149, 31, v148
	v_ashrrev_i32_e32 v145, 31, v144
	v_lshl_add_u64 v[172:173], v[164:165], 2, s[12:13]
	v_lshl_add_u64 v[174:175], v[160:161], 2, s[12:13]
	v_lshl_add_u64 v[176:177], v[156:157], 2, s[12:13]
	v_lshl_add_u64 v[178:179], v[152:153], 2, s[12:13]
	v_lshl_add_u64 v[180:181], v[148:149], 2, s[12:13]
	v_lshl_add_u64 v[182:183], v[144:145], 2, s[12:13]
	global_load_dword v145, v[166:167], off
	global_load_dword v149, v[172:173], off
	global_load_dword v153, v[174:175], off
	global_load_dword v154, v[176:177], off
	global_load_dword v157, v[178:179], off
	global_load_dword v158, v[180:181], off
	global_load_dword v161, v[182:183], off
	s_lshl_b32 s27, s55, 7
	v_ashrrev_i32_e32 v146, 1, v146
	s_or_b32 s27, s27, s22
	v_and_b32_e32 v146, -8, v146
	v_add_u32_e32 v172, s27, v146
	v_ashrrev_i32_e32 v173, 31, v172
	s_mov_b64 s[8:9], -1
	s_waitcnt vmcnt(0)
	v_fmamk_f32 v146, v150, 0x3a800000, v163
	v_rsq_f32_e32 v174, v146
	v_fmamk_f32 v145, v145, 0x3a800000, v163
	v_fmamk_f32 v146, v149, 0x3a800000, v163
	v_fmamk_f32 v149, v153, 0x3a800000, v163
	v_fmamk_f32 v150, v154, 0x3a800000, v163
	v_fmamk_f32 v153, v157, 0x3a800000, v163
	v_fmamk_f32 v157, v158, 0x3a800000, v163
	v_fmamk_f32 v161, v161, 0x3a800000, v163
	v_pk_mul_f32 v[124:125], v[124:125], v[174:175] op_sel_hi:[1,0]
	v_pk_mul_f32 v[126:127], v[126:127], v[174:175] op_sel_hi:[1,0]
	v_pk_mul_f32 v[120:121], v[120:121], v[174:175] op_sel_hi:[1,0]
	v_rsq_f32_e32 v176, v145
	v_rsq_f32_e32 v166, v146
	v_rsq_f32_e32 v162, v149
	v_rsq_f32_e32 v158, v150
	v_rsq_f32_e32 v154, v153
	v_rsq_f32_e32 v150, v157
	v_rsq_f32_e32 v146, v161
	v_pk_mul_f32 v[122:123], v[122:123], v[174:175] op_sel_hi:[1,0]
	v_mul_f32_e32 v145, 0xbfb8aa3b, v124
	v_mul_f32_e32 v149, 0xbfb8aa3b, v125
	v_mul_f32_e32 v153, 0xbfb8aa3b, v126
	v_mul_f32_e32 v157, 0xbfb8aa3b, v127
	v_mul_f32_e32 v161, 0xbfb8aa3b, v120
	v_mul_f32_e32 v165, 0xbfb8aa3b, v121
	v_mul_f32_e32 v167, 0xbfb8aa3b, v122
	v_mul_f32_e32 v169, 0xbfb8aa3b, v123
	v_exp_f32_e32 v145, v145
	v_exp_f32_e32 v149, v149
	v_exp_f32_e32 v153, v153
	v_exp_f32_e32 v157, v157
	v_exp_f32_e32 v161, v161
	v_exp_f32_e32 v165, v165
	v_exp_f32_e32 v167, v167
	v_exp_f32_e32 v169, v169
	v_add_f32_e32 v145, 1.0, v145
	v_add_f32_e32 v149, 1.0, v149
	v_add_f32_e32 v153, 1.0, v153
	v_add_f32_e32 v157, 1.0, v157
	v_add_f32_e32 v161, 1.0, v161
	v_add_f32_e32 v165, 1.0, v165
	v_add_f32_e32 v167, 1.0, v167
	v_add_f32_e32 v169, 1.0, v169
	v_rcp_f32_e32 v178, v145
	v_rcp_f32_e32 v179, v149
	v_rcp_f32_e32 v180, v153
	v_rcp_f32_e32 v181, v157
	v_rcp_f32_e32 v182, v161
	v_rcp_f32_e32 v183, v165
	v_rcp_f32_e32 v184, v167
	v_rcp_f32_e32 v185, v169
	v_pk_mul_f32 v[116:117], v[116:117], v[174:175] op_sel_hi:[1,0]
	v_pk_mul_f32 v[118:119], v[118:119], v[174:175] op_sel_hi:[1,0]
	v_pk_mul_f32 v[112:113], v[112:113], v[174:175] op_sel_hi:[1,0]
	v_pk_mul_f32 v[124:125], v[124:125], v[178:179]
	v_pk_mul_f32 v[126:127], v[126:127], v[180:181]
	v_pk_mul_f32 v[120:121], v[120:121], v[182:183]
	v_pk_mul_f32 v[116:117], v[116:117], v[124:125]
	v_pk_mul_f32 v[118:119], v[118:119], v[126:127]
	v_pk_mul_f32 v[112:113], v[112:113], v[120:121]
	v_pk_mul_f32 v[120:121], v[122:123], v[184:185]
	v_pk_mul_f32 v[114:115], v[114:115], v[174:175] op_sel_hi:[1,0]
	v_cvt_pk_bf16_f32 v116, v116, v117
	v_pk_mul_f32 v[114:115], v[114:115], v[120:121]
	v_cvt_pk_bf16_f32 v117, v118, v119
	v_cvt_pk_bf16_f32 v118, v112, v113
	v_mov_b64_e32 v[112:113], s[14:15]
	v_cvt_pk_bf16_f32 v119, v114, v115
	v_mad_i64_i32 v[120:121], s[38:39], v170, s49, v[112:113]
	v_lshlrev_b64 v[114:115], 1, v[172:173]
	v_pk_mul_f32 v[108:109], v[108:109], v[176:177] op_sel_hi:[1,0]
	v_lshl_add_u64 v[120:121], v[120:121], 0, v[114:115]
	v_mul_f32_e32 v122, 0xbfb8aa3b, v108
	v_mul_f32_e32 v123, 0xbfb8aa3b, v109
	v_pk_mul_f32 v[110:111], v[110:111], v[176:177] op_sel_hi:[1,0]
	v_exp_f32_e32 v122, v122
	v_exp_f32_e32 v123, v123
	global_store_dwordx4 v[120:121], v[116:119], off nt
	v_pk_mul_f32 v[100:101], v[100:101], v[176:177] op_sel_hi:[1,0]
	v_pk_mul_f32 v[104:105], v[104:105], v[176:177] op_sel_hi:[1,0]
	v_mul_f32_e32 v118, 0xbfb8aa3b, v110
	v_mul_f32_e32 v119, 0xbfb8aa3b, v111
	v_exp_f32_e32 v118, v118
	v_exp_f32_e32 v119, v119
	v_add_f32_e32 v116, 1.0, v122
	v_add_f32_e32 v117, 1.0, v123
	v_rcp_f32_e32 v116, v116
	v_rcp_f32_e32 v117, v117
	v_add_f32_e32 v118, 1.0, v118
	v_add_f32_e32 v119, 1.0, v119
	v_rcp_f32_e32 v118, v118
	v_rcp_f32_e32 v119, v119
	v_pk_mul_f32 v[108:109], v[108:109], v[116:117]
	v_pk_mul_f32 v[102:103], v[102:103], v[176:177] op_sel_hi:[1,0]
	v_pk_mul_f32 v[100:101], v[100:101], v[108:109]
	v_pk_mul_f32 v[108:109], v[110:111], v[118:119]
	v_mul_f32_e32 v110, 0xbfb8aa3b, v104
	v_mul_f32_e32 v111, 0xbfb8aa3b, v105
	v_exp_f32_e32 v110, v110
	v_exp_f32_e32 v111, v111
	v_pk_mul_f32 v[106:107], v[106:107], v[176:177] op_sel_hi:[1,0]
	v_pk_mul_f32 v[102:103], v[102:103], v[108:109]
; DI float silu(float x) { return x * sigm(x); }
; DI u32x4 pack8(f32x4 a, f32x4 b) { u32x4 w; w.x = pk2(a[0], a[1]); w.y = pk2(a[2], a[3]); w.z = pk2(b[0], b[1]); w.w = pk2(b[2], b[3]); return w; }
; #define EPI_ROWS(ai, m) _Pragma("unroll") for (int ai = 0; ai < 2; ++ai) _Pragma("unroll") for (int m = 0; m < 4; ++m)
;     DI void operator()(const Acc& acc, const Unit& u, int wr, int wc, int fr, int fq) const {
;     ...
;         EPI_ROWS(ai, m) { const int row = epi_row(u, ai, wr, m, fr); const float r = rr[ai][m];
;             f32x4 v[2];
; #pragma unroll
;             for (int n = 0; n < 2; ++n)
; #pragma unroll
;                 for (int j = 0; j < 4; ++j) v[n][j] = silu(acc[ai][0][m][n][j] * r) * (acc[ai][1][m][n][j] * r);
;             *(u32x4*)(act + (size_t)row * FF + cb) = pack8(v[0], v[1]); }
	v_add_f32_e32 v108, 1.0, v110
	v_add_f32_e32 v109, 1.0, v111
	v_mul_f32_e32 v110, 0xbfb8aa3b, v106
	v_mul_f32_e32 v111, 0xbfb8aa3b, v107
	v_exp_f32_e32 v110, v110
	v_exp_f32_e32 v111, v111
	v_rcp_f32_e32 v108, v108
	v_rcp_f32_e32 v109, v109
	v_add_f32_e32 v110, 1.0, v110
	v_add_f32_e32 v111, 1.0, v111
	v_rcp_f32_e32 v110, v110
	v_rcp_f32_e32 v111, v111
	v_pk_mul_f32 v[104:105], v[104:105], v[108:109]
	v_pk_mul_f32 v[96:97], v[96:97], v[176:177] op_sel_hi:[1,0]
	v_pk_mul_f32 v[98:99], v[98:99], v[176:177] op_sel_hi:[1,0]
	v_pk_mul_f32 v[104:105], v[96:97], v[104:105]
	v_pk_mul_f32 v[96:97], v[106:107], v[110:111]
	v_pk_mul_f32 v[92:93], v[92:93], v[166:167] op_sel_hi:[1,0]
	v_pk_mul_f32 v[106:107], v[98:99], v[96:97]
	v_cvt_pk_bf16_f32 v96, v100, v101
	v_mad_i64_i32 v[100:101], s[38:39], v168, s49, v[112:113]
	v_cvt_pk_bf16_f32 v97, v102, v103
	v_cvt_pk_bf16_f32 v98, v104, v105
	v_cvt_pk_bf16_f32 v99, v106, v107
	v_lshl_add_u64 v[100:101], v[100:101], 0, v[114:115]
	v_mul_f32_e32 v102, 0xbfb8aa3b, v92
	v_mul_f32_e32 v103, 0xbfb8aa3b, v93
	v_pk_mul_f32 v[94:95], v[94:95], v[166:167] op_sel_hi:[1,0]
	v_exp_f32_e32 v102, v102
	v_exp_f32_e32 v103, v103
	global_store_dwordx4 v[100:101], v[96:99], off nt
	v_pk_mul_f32 v[84:85], v[84:85], v[166:167] op_sel_hi:[1,0]
	v_pk_mul_f32 v[88:89], v[88:89], v[166:167] op_sel_hi:[1,0]
	v_mul_f32_e32 v98, 0xbfb8aa3b, v94
	v_mul_f32_e32 v99, 0xbfb8aa3b, v95
	v_exp_f32_e32 v98, v98
	v_exp_f32_e32 v99, v99
	v_add_f32_e32 v96, 1.0, v102
	v_add_f32_e32 v97, 1.0, v103
	v_rcp_f32_e32 v96, v96
	v_rcp_f32_e32 v97, v97
	v_add_f32_e32 v98, 1.0, v98
	v_add_f32_e32 v99, 1.0, v99
	v_rcp_f32_e32 v98, v98
	v_rcp_f32_e32 v99, v99
	v_pk_mul_f32 v[92:93], v[92:93], v[96:97]
	v_pk_mul_f32 v[86:87], v[86:87], v[166:167] op_sel_hi:[1,0]
	v_pk_mul_f32 v[84:85], v[84:85], v[92:93]
	v_pk_mul_f32 v[92:93], v[94:95], v[98:99]
	v_mul_f32_e32 v94, 0xbfb8aa3b, v88
	v_mul_f32_e32 v95, 0xbfb8aa3b, v89
	v_exp_f32_e32 v94, v94
	v_exp_f32_e32 v95, v95
	v_pk_mul_f32 v[90:91], v[90:91], v[166:167] op_sel_hi:[1,0]
	v_pk_mul_f32 v[86:87], v[86:87], v[92:93]
	v_add_f32_e32 v92, 1.0, v94
	v_add_f32_e32 v93, 1.0, v95
	v_mul_f32_e32 v94, 0xbfb8aa3b, v90
	v_mul_f32_e32 v95, 0xbfb8aa3b, v91
	v_exp_f32_e32 v94, v94
	v_exp_f32_e32 v95, v95
	v_rcp_f32_e32 v92, v92
	v_rcp_f32_e32 v93, v93
	v_add_f32_e32 v94, 1.0, v94
	v_add_f32_e32 v95, 1.0, v95
	v_rcp_f32_e32 v94, v94
	v_rcp_f32_e32 v95, v95
	v_pk_mul_f32 v[88:89], v[88:89], v[92:93]
	v_pk_mul_f32 v[80:81], v[80:81], v[166:167] op_sel_hi:[1,0]
	v_pk_mul_f32 v[82:83], v[82:83], v[166:167] op_sel_hi:[1,0]
	v_pk_mul_f32 v[88:89], v[80:81], v[88:89]
	v_pk_mul_f32 v[80:81], v[90:91], v[94:95]
	v_pk_mul_f32 v[76:77], v[76:77], v[162:163] op_sel_hi:[1,0]
	v_pk_mul_f32 v[90:91], v[82:83], v[80:81]
	v_cvt_pk_bf16_f32 v80, v84, v85
	v_mad_i64_i32 v[84:85], s[38:39], v164, s49, v[112:113]
	v_cvt_pk_bf16_f32 v81, v86, v87
	v_cvt_pk_bf16_f32 v82, v88, v89
	v_cvt_pk_bf16_f32 v83, v90, v91
	v_lshl_add_u64 v[84:85], v[84:85], 0, v[114:115]
	v_mul_f32_e32 v86, 0xbfb8aa3b, v76
	v_mul_f32_e32 v87, 0xbfb8aa3b, v77
	v_pk_mul_f32 v[78:79], v[78:79], v[162:163] op_sel_hi:[1,0]
	v_exp_f32_e32 v86, v86
	v_exp_f32_e32 v87, v87
	global_store_dwordx4 v[84:85], v[80:83], off nt
	v_pk_mul_f32 v[68:69], v[68:69], v[162:163] op_sel_hi:[1,0]
	v_pk_mul_f32 v[72:73], v[72:73], v[162:163] op_sel_hi:[1,0]
	v_mul_f32_e32 v82, 0xbfb8aa3b, v78
	v_mul_f32_e32 v83, 0xbfb8aa3b, v79
	v_exp_f32_e32 v82, v82
	v_exp_f32_e32 v83, v83
	v_add_f32_e32 v80, 1.0, v86
	v_add_f32_e32 v81, 1.0, v87
	v_rcp_f32_e32 v80, v80
	v_rcp_f32_e32 v81, v81
	v_add_f32_e32 v82, 1.0, v82
	v_add_f32_e32 v83, 1.0, v83
	v_rcp_f32_e32 v82, v82
	v_rcp_f32_e32 v83, v83
	v_pk_mul_f32 v[76:77], v[76:77], v[80:81]
	v_pk_mul_f32 v[70:71], v[70:71], v[162:163] op_sel_hi:[1,0]
	v_pk_mul_f32 v[68:69], v[68:69], v[76:77]
	v_pk_mul_f32 v[76:77], v[78:79], v[82:83]
	v_mul_f32_e32 v78, 0xbfb8aa3b, v72
	v_mul_f32_e32 v79, 0xbfb8aa3b, v73
	v_exp_f32_e32 v78, v78
	v_exp_f32_e32 v79, v79
	v_pk_mul_f32 v[74:75], v[74:75], v[162:163] op_sel_hi:[1,0]
	v_pk_mul_f32 v[70:71], v[70:71], v[76:77]
	v_add_f32_e32 v76, 1.0, v78
	v_add_f32_e32 v77, 1.0, v79
	v_mul_f32_e32 v78, 0xbfb8aa3b, v74
	v_mul_f32_e32 v79, 0xbfb8aa3b, v75
	v_exp_f32_e32 v78, v78
	v_exp_f32_e32 v79, v79
	v_rcp_f32_e32 v76, v76
	v_rcp_f32_e32 v77, v77
	v_add_f32_e32 v78, 1.0, v78
	v_add_f32_e32 v79, 1.0, v79
	v_rcp_f32_e32 v78, v78
	v_rcp_f32_e32 v79, v79
	v_pk_mul_f32 v[72:73], v[72:73], v[76:77]
	v_pk_mul_f32 v[64:65], v[64:65], v[162:163] op_sel_hi:[1,0]
	v_pk_mul_f32 v[66:67], v[66:67], v[162:163] op_sel_hi:[1,0]
	v_pk_mul_f32 v[72:73], v[64:65], v[72:73]
	v_pk_mul_f32 v[64:65], v[74:75], v[78:79]
	v_pk_mul_f32 v[60:61], v[60:61], v[158:159] op_sel_hi:[1,0]
	v_pk_mul_f32 v[74:75], v[66:67], v[64:65]
	v_cvt_pk_bf16_f32 v64, v68, v69
	v_mad_i64_i32 v[68:69], s[38:39], v160, s49, v[112:113]
	v_cvt_pk_bf16_f32 v65, v70, v71
	v_cvt_pk_bf16_f32 v66, v72, v73
	v_cvt_pk_bf16_f32 v67, v74, v75
	v_lshl_add_u64 v[68:69], v[68:69], 0, v[114:115]
	v_mul_f32_e32 v70, 0xbfb8aa3b, v60
	v_mul_f32_e32 v71, 0xbfb8aa3b, v61
	v_pk_mul_f32 v[62:63], v[62:63], v[158:159] op_sel_hi:[1,0]
	v_exp_f32_e32 v70, v70
	v_exp_f32_e32 v71, v71
	global_store_dwordx4 v[68:69], v[64:67], off nt
	v_pk_mul_f32 v[52:53], v[52:53], v[158:159] op_sel_hi:[1,0]
	v_pk_mul_f32 v[56:57], v[56:57], v[158:159] op_sel_hi:[1,0]
	v_mul_f32_e32 v66, 0xbfb8aa3b, v62
	v_mul_f32_e32 v67, 0xbfb8aa3b, v63
	v_exp_f32_e32 v66, v66
	v_exp_f32_e32 v67, v67
	v_add_f32_e32 v64, 1.0, v70
	v_add_f32_e32 v65, 1.0, v71
	v_rcp_f32_e32 v64, v64
	v_rcp_f32_e32 v65, v65
	v_add_f32_e32 v66, 1.0, v66
; DI float silu(float x) { return x * sigm(x); }
; DI u32x4 pack8(f32x4 a, f32x4 b) { u32x4 w; w.x = pk2(a[0], a[1]); w.y = pk2(a[2], a[3]); w.z = pk2(b[0], b[1]); w.w = pk2(b[2], b[3]); return w; }
; #define EPI_ROWS(ai, m) _Pragma("unroll") for (int ai = 0; ai < 2; ++ai) _Pragma("unroll") for (int m = 0; m < 4; ++m)
;     DI void operator()(const Acc& acc, const Unit& u, int wr, int wc, int fr, int fq) const {
;     ...
;         EPI_ROWS(ai, m) { const int row = epi_row(u, ai, wr, m, fr); const float r = rr[ai][m];
;             f32x4 v[2];
; #pragma unroll
;             for (int n = 0; n < 2; ++n)
; #pragma unroll
;                 for (int j = 0; j < 4; ++j) v[n][j] = silu(acc[ai][0][m][n][j] * r) * (acc[ai][1][m][n][j] * r);
;             *(u32x4*)(act + (size_t)row * FF + cb) = pack8(v[0], v[1]); }
	v_add_f32_e32 v67, 1.0, v67
	v_rcp_f32_e32 v66, v66
	v_rcp_f32_e32 v67, v67
	v_pk_mul_f32 v[60:61], v[60:61], v[64:65]
	v_pk_mul_f32 v[54:55], v[54:55], v[158:159] op_sel_hi:[1,0]
	v_pk_mul_f32 v[52:53], v[52:53], v[60:61]
	v_pk_mul_f32 v[60:61], v[62:63], v[66:67]
	v_mul_f32_e32 v62, 0xbfb8aa3b, v56
	v_mul_f32_e32 v63, 0xbfb8aa3b, v57
	v_exp_f32_e32 v62, v62
	v_exp_f32_e32 v63, v63
	v_pk_mul_f32 v[58:59], v[58:59], v[158:159] op_sel_hi:[1,0]
	v_pk_mul_f32 v[54:55], v[54:55], v[60:61]
	v_add_f32_e32 v60, 1.0, v62
	v_add_f32_e32 v61, 1.0, v63
	v_mul_f32_e32 v62, 0xbfb8aa3b, v58
	v_mul_f32_e32 v63, 0xbfb8aa3b, v59
	v_exp_f32_e32 v62, v62
	v_exp_f32_e32 v63, v63
	v_rcp_f32_e32 v60, v60
	v_rcp_f32_e32 v61, v61
	v_add_f32_e32 v62, 1.0, v62
	v_add_f32_e32 v63, 1.0, v63
	v_rcp_f32_e32 v62, v62
	v_rcp_f32_e32 v63, v63
	v_pk_mul_f32 v[56:57], v[56:57], v[60:61]
	v_pk_mul_f32 v[48:49], v[48:49], v[158:159] op_sel_hi:[1,0]
	v_pk_mul_f32 v[50:51], v[50:51], v[158:159] op_sel_hi:[1,0]
	v_pk_mul_f32 v[56:57], v[48:49], v[56:57]
	v_pk_mul_f32 v[48:49], v[58:59], v[62:63]
	v_pk_mul_f32 v[44:45], v[44:45], v[154:155] op_sel_hi:[1,0]
	v_pk_mul_f32 v[58:59], v[50:51], v[48:49]
	v_cvt_pk_bf16_f32 v48, v52, v53
	v_mad_i64_i32 v[52:53], s[38:39], v156, s49, v[112:113]
	v_cvt_pk_bf16_f32 v49, v54, v55
	v_cvt_pk_bf16_f32 v50, v56, v57
	v_cvt_pk_bf16_f32 v51, v58, v59
	v_lshl_add_u64 v[52:53], v[52:53], 0, v[114:115]
	v_mul_f32_e32 v54, 0xbfb8aa3b, v44
	v_mul_f32_e32 v55, 0xbfb8aa3b, v45
	v_pk_mul_f32 v[46:47], v[46:47], v[154:155] op_sel_hi:[1,0]
	v_exp_f32_e32 v54, v54
	v_exp_f32_e32 v55, v55
	global_store_dwordx4 v[52:53], v[48:51], off nt
	v_pk_mul_f32 v[36:37], v[36:37], v[154:155] op_sel_hi:[1,0]
	v_pk_mul_f32 v[40:41], v[40:41], v[154:155] op_sel_hi:[1,0]
	v_mul_f32_e32 v50, 0xbfb8aa3b, v46
	v_mul_f32_e32 v51, 0xbfb8aa3b, v47
	v_exp_f32_e32 v50, v50
	v_exp_f32_e32 v51, v51
	v_add_f32_e32 v48, 1.0, v54
	v_add_f32_e32 v49, 1.0, v55
	v_rcp_f32_e32 v48, v48
	v_rcp_f32_e32 v49, v49
	v_add_f32_e32 v50, 1.0, v50
	v_add_f32_e32 v51, 1.0, v51
	v_rcp_f32_e32 v50, v50
	v_rcp_f32_e32 v51, v51
	v_pk_mul_f32 v[44:45], v[44:45], v[48:49]
	v_pk_mul_f32 v[38:39], v[38:39], v[154:155] op_sel_hi:[1,0]
	v_pk_mul_f32 v[36:37], v[36:37], v[44:45]
	v_pk_mul_f32 v[44:45], v[46:47], v[50:51]
	v_mul_f32_e32 v46, 0xbfb8aa3b, v40
	v_mul_f32_e32 v47, 0xbfb8aa3b, v41
	v_exp_f32_e32 v46, v46
	v_exp_f32_e32 v47, v47
	v_pk_mul_f32 v[42:43], v[42:43], v[154:155] op_sel_hi:[1,0]
	v_pk_mul_f32 v[38:39], v[38:39], v[44:45]
	v_add_f32_e32 v44, 1.0, v46
	v_add_f32_e32 v45, 1.0, v47
	v_mul_f32_e32 v46, 0xbfb8aa3b, v42
	v_mul_f32_e32 v47, 0xbfb8aa3b, v43
	v_exp_f32_e32 v46, v46
	v_exp_f32_e32 v47, v47
	v_rcp_f32_e32 v44, v44
	v_rcp_f32_e32 v45, v45
	v_add_f32_e32 v46, 1.0, v46
	v_add_f32_e32 v47, 1.0, v47
	v_rcp_f32_e32 v46, v46
	v_rcp_f32_e32 v47, v47
	v_pk_mul_f32 v[40:41], v[40:41], v[44:45]
	v_pk_mul_f32 v[32:33], v[32:33], v[154:155] op_sel_hi:[1,0]
	v_pk_mul_f32 v[34:35], v[34:35], v[154:155] op_sel_hi:[1,0]
	v_pk_mul_f32 v[40:41], v[32:33], v[40:41]
	v_pk_mul_f32 v[32:33], v[42:43], v[46:47]
	v_pk_mul_f32 v[28:29], v[28:29], v[150:151] op_sel_hi:[1,0]
	v_pk_mul_f32 v[42:43], v[34:35], v[32:33]
	v_cvt_pk_bf16_f32 v32, v36, v37
	v_mad_i64_i32 v[36:37], s[38:39], v152, s49, v[112:113]
	v_cvt_pk_bf16_f32 v33, v38, v39
	v_cvt_pk_bf16_f32 v34, v40, v41
	v_cvt_pk_bf16_f32 v35, v42, v43
	v_lshl_add_u64 v[36:37], v[36:37], 0, v[114:115]
	v_mul_f32_e32 v38, 0xbfb8aa3b, v28
	v_mul_f32_e32 v39, 0xbfb8aa3b, v29
	v_pk_mul_f32 v[30:31], v[30:31], v[150:151] op_sel_hi:[1,0]
	v_exp_f32_e32 v38, v38
	v_exp_f32_e32 v39, v39
	global_store_dwordx4 v[36:37], v[32:35], off nt
	v_pk_mul_f32 v[20:21], v[20:21], v[150:151] op_sel_hi:[1,0]
	v_pk_mul_f32 v[24:25], v[24:25], v[150:151] op_sel_hi:[1,0]
; DI float silu(float x) { return x * sigm(x); }
; DI int lane_id() { int l; asm volatile("v_mbcnt_lo_u32_b32 %0, -1, 0\n\tv_mbcnt_hi_u32_b32 %0, -1, %0" : "=v"(l)); return l; }
; DI u32x4 pack8(f32x4 a, f32x4 b) { u32x4 w; w.x = pk2(a[0], a[1]); w.y = pk2(a[2], a[3]); w.z = pk2(b[0], b[1]); w.w = pk2(b[2], b[3]); return w; }
; #define PG8_BAR __builtin_amdgcn_s_barrier()
; #define EPI_ROWS(ai, m) _Pragma("unroll") for (int ai = 0; ai < 2; ++ai) _Pragma("unroll") for (int m = 0; m < 4; ++m)
; template <class Epi>
; DI void gemm_phase(LAS unsigned char* lds, const int wid, const Gemm g, const Order& S, const Epi& E) {
;     ...
;         if (wr == 0) PG8_BAR;
;         { const int le = lane_id(); E(acc, cur, wr, wc, le & 15, le >> 4); }
;         if (!has_next) break;
; #pragma unroll
;         for (int a = 0; a < 2; ++a)
; #pragma unroll
;             for (int b = 0; b < 2; ++b)
; #pragma unroll
;                 for (int m = 0; m < 4; ++m)
; #pragma unroll
;                     for (int n = 0; n < 2; ++n) acc[a][b][m][n] = (f32x4){0.f, 0.f, 0.f, 0.f};
;         cur = nxt; cA = nA; cB = nB; ++ui;
;         if (wr == 1) PG8_BAR;
;     DI void operator()(const Acc& acc, const Unit& u, int wr, int wc, int fr, int fq) const {
;     ...
;         EPI_ROWS(ai, m) { const int row = epi_row(u, ai, wr, m, fr); const float r = rr[ai][m];
;             f32x4 v[2];
; #pragma unroll
;             for (int n = 0; n < 2; ++n)
; #pragma unroll
;                 for (int j = 0; j < 4; ++j) v[n][j] = silu(acc[ai][0][m][n][j] * r) * (acc[ai][1][m][n][j] * r);
;             *(u32x4*)(act + (size_t)row * FF + cb) = pack8(v[0], v[1]); }
	v_mul_f32_e32 v34, 0xbfb8aa3b, v30
	v_mul_f32_e32 v35, 0xbfb8aa3b, v31
	v_exp_f32_e32 v34, v34
	v_exp_f32_e32 v35, v35
	v_add_f32_e32 v32, 1.0, v38
	v_add_f32_e32 v33, 1.0, v39
	v_rcp_f32_e32 v32, v32
	v_rcp_f32_e32 v33, v33
	v_add_f32_e32 v34, 1.0, v34
	v_add_f32_e32 v35, 1.0, v35
	v_rcp_f32_e32 v34, v34
	v_rcp_f32_e32 v35, v35
	v_pk_mul_f32 v[28:29], v[28:29], v[32:33]
	v_pk_mul_f32 v[22:23], v[22:23], v[150:151] op_sel_hi:[1,0]
	v_pk_mul_f32 v[20:21], v[20:21], v[28:29]
	v_pk_mul_f32 v[28:29], v[30:31], v[34:35]
	v_mul_f32_e32 v30, 0xbfb8aa3b, v24
	v_mul_f32_e32 v31, 0xbfb8aa3b, v25
	v_exp_f32_e32 v30, v30
	v_exp_f32_e32 v31, v31
	v_pk_mul_f32 v[26:27], v[26:27], v[150:151] op_sel_hi:[1,0]
	v_pk_mul_f32 v[22:23], v[22:23], v[28:29]
	v_add_f32_e32 v28, 1.0, v30
	v_add_f32_e32 v29, 1.0, v31
	v_mul_f32_e32 v30, 0xbfb8aa3b, v26
	v_mul_f32_e32 v31, 0xbfb8aa3b, v27
	v_exp_f32_e32 v30, v30
	v_exp_f32_e32 v31, v31
	v_rcp_f32_e32 v28, v28
	v_rcp_f32_e32 v29, v29
	v_add_f32_e32 v30, 1.0, v30
	v_add_f32_e32 v31, 1.0, v31
	v_rcp_f32_e32 v30, v30
	v_rcp_f32_e32 v31, v31
	v_pk_mul_f32 v[24:25], v[24:25], v[28:29]
	v_pk_mul_f32 v[16:17], v[16:17], v[150:151] op_sel_hi:[1,0]
	v_pk_mul_f32 v[18:19], v[18:19], v[150:151] op_sel_hi:[1,0]
	v_pk_mul_f32 v[24:25], v[16:17], v[24:25]
	v_pk_mul_f32 v[16:17], v[26:27], v[30:31]
	v_pk_mul_f32 v[12:13], v[12:13], v[146:147] op_sel_hi:[1,0]
	v_pk_mul_f32 v[26:27], v[18:19], v[16:17]
	v_cvt_pk_bf16_f32 v16, v20, v21
	v_mad_i64_i32 v[20:21], s[38:39], v148, s49, v[112:113]
	v_cvt_pk_bf16_f32 v17, v22, v23
	v_cvt_pk_bf16_f32 v18, v24, v25
	v_cvt_pk_bf16_f32 v19, v26, v27
	v_lshl_add_u64 v[20:21], v[20:21], 0, v[114:115]
	v_mul_f32_e32 v22, 0xbfb8aa3b, v12
	v_mul_f32_e32 v23, 0xbfb8aa3b, v13
	v_pk_mul_f32 v[14:15], v[14:15], v[146:147] op_sel_hi:[1,0]
	v_exp_f32_e32 v22, v22
	v_exp_f32_e32 v23, v23
	global_store_dwordx4 v[20:21], v[16:19], off nt
	v_pk_mul_f32 v[4:5], v[4:5], v[146:147] op_sel_hi:[1,0]
	v_pk_mul_f32 v[8:9], v[8:9], v[146:147] op_sel_hi:[1,0]
	v_mul_f32_e32 v18, 0xbfb8aa3b, v14
	v_mul_f32_e32 v19, 0xbfb8aa3b, v15
	v_exp_f32_e32 v18, v18
	v_exp_f32_e32 v19, v19
	v_add_f32_e32 v16, 1.0, v22
	v_add_f32_e32 v17, 1.0, v23
	v_rcp_f32_e32 v16, v16
	v_rcp_f32_e32 v17, v17
	v_add_f32_e32 v18, 1.0, v18
	v_add_f32_e32 v19, 1.0, v19
	v_rcp_f32_e32 v18, v18
	v_rcp_f32_e32 v19, v19
	v_pk_mul_f32 v[12:13], v[12:13], v[16:17]
	v_pk_mul_f32 v[6:7], v[6:7], v[146:147] op_sel_hi:[1,0]
	v_pk_mul_f32 v[4:5], v[4:5], v[12:13]
	v_pk_mul_f32 v[12:13], v[14:15], v[18:19]
	v_mul_f32_e32 v14, 0xbfb8aa3b, v8
	v_mul_f32_e32 v15, 0xbfb8aa3b, v9
	v_exp_f32_e32 v14, v14
	v_exp_f32_e32 v15, v15
	v_pk_mul_f32 v[10:11], v[10:11], v[146:147] op_sel_hi:[1,0]
	v_pk_mul_f32 v[6:7], v[6:7], v[12:13]
	v_add_f32_e32 v12, 1.0, v14
	v_add_f32_e32 v13, 1.0, v15
	v_mul_f32_e32 v14, 0xbfb8aa3b, v10
	v_mul_f32_e32 v15, 0xbfb8aa3b, v11
	v_exp_f32_e32 v14, v14
	v_exp_f32_e32 v15, v15
	v_rcp_f32_e32 v12, v12
	v_rcp_f32_e32 v13, v13
	v_add_f32_e32 v14, 1.0, v14
	v_add_f32_e32 v15, 1.0, v15
	v_rcp_f32_e32 v14, v14
	v_rcp_f32_e32 v15, v15
	v_pk_mul_f32 v[8:9], v[8:9], v[12:13]
	v_pk_mul_f32 v[0:1], v[0:1], v[146:147] op_sel_hi:[1,0]
	v_pk_mul_f32 v[2:3], v[2:3], v[146:147] op_sel_hi:[1,0]
	v_pk_mul_f32 v[8:9], v[0:1], v[8:9]
	v_pk_mul_f32 v[0:1], v[10:11], v[14:15]
	s_nop 0
	v_pk_mul_f32 v[10:11], v[2:3], v[0:1]
	v_cvt_pk_bf16_f32 v0, v4, v5
	v_mad_i64_i32 v[4:5], s[38:39], v144, s49, v[112:113]
	v_cvt_pk_bf16_f32 v1, v6, v7
	v_cvt_pk_bf16_f32 v2, v8, v9
	v_cvt_pk_bf16_f32 v3, v10, v11
	v_lshl_add_u64 v[4:5], v[4:5], 0, v[114:115]
	global_store_dwordx4 v[4:5], v[0:3], off nt
	s_cbranch_vccnz .LBB0_1332
	s_andn2_b64 vcc, exec, s[10:11]
	s_cbranch_vccnz .LBB0_1331
	s_barrier
	s_branch .LBB0_1331
